# ph_shw: the shift-vector LDS staging is done once per workgroup, later items reuse it
# speedup vs baseline: 1.0053x; 1.0012x over previous
; DEVI void ph_shw(const int wv, const Params& p, int l, unsigned char* lds, int blk_lo) {
;     ...
;     float* shv = (float*)lds;
;     float* red = shv + 17 * 1024;
;     const float* mod = (const float*)(p.ws + OFF_MOD) + (size_t)l * 17 * 6144;
;     for (int e = bx * NTHREADS + tid; e < 17 * 1024; e += nbx * NTHREADS) { const int r = e >> 10, k = e & 1023;
;         ((float*)(p.ws + OFF_A2))[(size_t)l * 17 * 1024 + e] = p.in[5][l * 1024 + k] * (1.0f + mod[(size_t)r * 6144 + 4096 + k]); }
;     for (int it = bx; it < 256; it += nbx) {
;         const int n0 = it * 16;
;         __syncthreads();
;         for (int e = tid; e < 17 * 1024; e += NTHREADS) { const int r = e >> 10, k = e & 1023; shv[e] = mod[(size_t)r * 6144 + 3072 + k]; }
.LBB0_982:
	s_or_b64 exec, exec, s[0:1]
	v_readlane_b32 s0, v252, 43
	v_readlane_b32 s1, v252, 44
	s_movk_i32 s51, 0x8000
	s_mov_b32 s52, 0xffff0000
	s_movk_i32 s53, 0x41ff
	s_mov_b32 s54, 0xfffe4000
	s_mov_b32 s56, 0xfffe8000
	s_mov_b32 s57, 0xfffec000
	s_mov_b32 s58, 0xffff4000
	s_movk_i32 s59, 0xc000
	s_andn2_b64 vcc, exec, s[0:1]
	s_movk_i32 s55, 0xc00
	s_cbranch_vccnz .LBB0_1003
	v_lshlrev_b32_e32 v3, 2, v6
	v_max_i32_e32 v6, 0xffffff10, v74
	v_max_i32_e32 v8, 0x4200, v74
	v_ashrrev_i32_e32 v4, 4, v74
	v_sub_u32_e32 v6, v6, v74
	v_sub_u32_e32 v8, v8, v74
	v_lshlrev_b32_e32 v2, 5, v4
	v_add_u32_e32 v6, 0x1ff, v6
	v_add_u32_e32 v8, 0x1ff, v8
	v_readlane_b32 s12, v253, 3
	v_and_b32_e32 v0, 60, v3
	s_movk_i32 s4, 0x440
	v_lshrrev_b32_e32 v7, 9, v6
	v_lshrrev_b32_e32 v9, 9, v8
	v_add_u32_e32 v101, s12, v3
	v_ashrrev_i32_e32 v3, 31, v2
	v_readlane_b32 s2, v253, 25
	v_mul_lo_u32 v5, v4, s4
	v_readlane_b32 s4, v252, 45
	v_add_u32_e32 v7, 1, v7
	v_add_u32_e32 v9, 1, v9
	v_lshlrev_b64 v[2:3], 14, v[2:3]
	v_readlane_b32 s12, v253, 10
	s_movk_i32 s0, 0x4400
	v_add_u32_e32 v96, s2, v0
	s_movk_i32 s2, 0x110
	v_readlane_b32 s5, v252, 46
	s_movk_i32 s8, 0x1ff
	v_and_b32_e32 v97, 0xfffffe, v9
	v_and_b32_e32 v99, 0xfffffe, v7
	v_or_b32_e32 v2, v2, v0
	v_readlane_b32 s13, v253, 11
	v_cmp_gt_i32_e64 s[0:1], s0, v74
	v_cmp_gt_i32_e64 s[2:3], s2, v74
	v_lshl_add_u64 v[76:77], s[4:5], 0, v[0:1]
	v_cmp_lt_u32_e64 s[4:5], s8, v8
	v_lshl_add_u32 v98, v97, 9, v74
	v_add_u32_e32 v75, 0x200, v74
	v_cmp_ne_u32_e64 s[6:7], v9, v97
	v_cmp_lt_u32_e64 s[8:9], s8, v6
	v_lshl_add_u32 v100, v99, 9, v74
	v_cmp_ne_u32_e64 s[10:11], v7, v99
	v_lshl_add_u64 v[78:79], s[12:13], 0, v[2:3]
	v_lshl_add_u32 v102, v4, 7, 0
	v_add_u32_e32 v103, v96, v5
	v_readlane_b32 s12, v253, 13
	v_readlane_b32 s18, v252, 38
	s_mov_b32 s100, 0
	s_branch .LBB0_985

; DEVI void ph_shw(const int wv, const Params& p, int l, unsigned char* lds, int blk_lo) {
;     ...
;     for (int it = bx; it < 256; it += nbx) {
;         const int n0 = it * 16;
;         __syncthreads();
;         for (int e = tid; e < 17 * 1024; e += NTHREADS) { const int r = e >> 10, k = e & 1023; shv[e] = mod[(size_t)r * 6144 + 3072 + k]; }
.LBB0_985:
	s_waitcnt vmcnt(0) lgkmcnt(0)
	s_barrier
	s_cmp_lg_u32 s100, 0
	s_mov_b32 s100, 1
	s_cbranch_scc1 .LBB0_993
	s_and_saveexec_b64 s[28:29], s[0:1]
	s_cbranch_execz .LBB0_993
	s_mov_b64 s[36:37], -1
	v_mov_b32_e32 v2, v74
	s_and_saveexec_b64 s[30:31], s[4:5]
	s_cbranch_execz .LBB0_990
	s_mov_b64 s[36:37], 0
	v_mov_b32_e32 v4, v97
	v_mov_b32_e32 v5, v101
	v_mov_b64_e32 v[2:3], v[74:75]
	s_movk_i32 s13, 0x3000

; DEVI void ph_shw(const int wv, const Params& p, int l, unsigned char* lds, int blk_lo) {
;     ...
;     float* shv = (float*)lds;
;     float* red = shv + 17 * 1024;
;     const float* mod = (const float*)(p.ws + OFF_MOD) + (size_t)l * 17 * 6144;
;     for (int e = bx * NTHREADS + tid; e < 17 * 1024; e += nbx * NTHREADS) { const int r = e >> 10, k = e & 1023;
;         ((float*)(p.ws + OFF_A2))[(size_t)l * 17 * 1024 + e] = p.in[5][l * 1024 + k] * (1.0f + mod[(size_t)r * 6144 + 4096 + k]); }
;     for (int it = bx; it < 256; it += nbx) {
;         const int n0 = it * 16;
;         __syncthreads();
;         for (int e = tid; e < 17 * 1024; e += NTHREADS) { const int r = e >> 10, k = e & 1023; shv[e] = mod[(size_t)r * 6144 + 3072 + k]; }
.LBB0_1195:
	s_or_b64 exec, exec, s[0:1]
	v_readlane_b32 s0, v252, 43
	v_readlane_b32 s1, v252, 44
	s_movk_i32 s40, 0x8000
	s_mov_b32 s41, 0xffff0000
	s_movk_i32 s51, 0x41ff
	s_mov_b32 s52, 0xfffe4000
	s_mov_b32 s53, 0xfffe8000
	s_mov_b32 s54, 0xfffec000
	s_mov_b32 s56, 0xffff4000
	s_movk_i32 s57, 0xc000
	s_andn2_b64 vcc, exec, s[0:1]
	s_movk_i32 s55, 0xc00
	s_cbranch_vccnz .LBB0_1216
	v_lshlrev_b32_e32 v3, 2, v6
	v_max_i32_e32 v6, 0xffffff10, v74
	v_max_i32_e32 v8, 0x4200, v74
	v_ashrrev_i32_e32 v4, 4, v74
	v_sub_u32_e32 v6, v6, v74
	v_sub_u32_e32 v8, v8, v74
	v_lshlrev_b32_e32 v2, 5, v4
	v_add_u32_e32 v6, 0x1ff, v6
	v_add_u32_e32 v8, 0x1ff, v8
	v_readlane_b32 s12, v253, 3
	v_and_b32_e32 v0, 60, v3
	s_movk_i32 s4, 0x440
	v_lshrrev_b32_e32 v7, 9, v6
	v_lshrrev_b32_e32 v9, 9, v8
	v_add_u32_e32 v101, s12, v3
	v_ashrrev_i32_e32 v3, 31, v2
	v_readlane_b32 s2, v253, 25
	v_mul_lo_u32 v5, v4, s4
	v_readlane_b32 s4, v252, 45
	v_add_u32_e32 v7, 1, v7
	v_add_u32_e32 v9, 1, v9
	v_lshlrev_b64 v[2:3], 14, v[2:3]
	v_readlane_b32 s12, v253, 19
	s_movk_i32 s0, 0x4400
	v_add_u32_e32 v96, s2, v0
	s_movk_i32 s2, 0x110
	v_readlane_b32 s5, v252, 46
	s_movk_i32 s8, 0x1ff
	v_and_b32_e32 v97, 0xfffffe, v9
	v_and_b32_e32 v99, 0xfffffe, v7
	v_or_b32_e32 v2, v2, v0
	v_readlane_b32 s13, v253, 20
	v_cmp_gt_i32_e64 s[0:1], s0, v74
	v_cmp_gt_i32_e64 s[2:3], s2, v74
	v_lshl_add_u64 v[76:77], s[4:5], 0, v[0:1]
	v_cmp_lt_u32_e64 s[4:5], s8, v8
	v_lshl_add_u32 v98, v97, 9, v74
	v_add_u32_e32 v75, 0x200, v74
	v_cmp_ne_u32_e64 s[6:7], v9, v97
	v_cmp_lt_u32_e64 s[8:9], s8, v6
	v_lshl_add_u32 v100, v99, 9, v74
	v_cmp_ne_u32_e64 s[10:11], v7, v99
	v_lshl_add_u64 v[78:79], s[12:13], 0, v[2:3]
	v_lshl_add_u32 v102, v4, 7, 0
	v_add_u32_e32 v103, v96, v5
	v_readlane_b32 s12, v253, 13
	v_readlane_b32 s18, v252, 38
	s_mov_b32 s100, 0
	s_branch .LBB0_1198

; DEVI void ph_shw(const int wv, const Params& p, int l, unsigned char* lds, int blk_lo) {
;     ...
;     for (int it = bx; it < 256; it += nbx) {
;         const int n0 = it * 16;
;         __syncthreads();
;         for (int e = tid; e < 17 * 1024; e += NTHREADS) { const int r = e >> 10, k = e & 1023; shv[e] = mod[(size_t)r * 6144 + 3072 + k]; }
.LBB0_1198:
	s_waitcnt vmcnt(0)
	s_barrier
	s_cmp_lg_u32 s100, 0
	s_mov_b32 s100, 1
	s_cbranch_scc1 .LBB0_1206
	s_and_saveexec_b64 s[28:29], s[0:1]
	s_cbranch_execz .LBB0_1206
	s_mov_b64 s[34:35], -1
	v_mov_b32_e32 v2, v74
	s_and_saveexec_b64 s[30:31], s[4:5]
	s_cbranch_execz .LBB0_1203
	s_mov_b64 s[34:35], 0
	v_mov_b32_e32 v4, v97
	v_mov_b32_e32 v5, v101
	v_mov_b64_e32 v[2:3], v[74:75]
	s_movk_i32 s13, 0x3000
